# latent attention chunk: batched LDS fragment reads for QK/PV with wave-uniform tile skipping, unconditional bias reads + select; K-norm lane sums via DPP
# speedup vs baseline: 1.0146x; 1.0097x over previous
.LBB0_453:
	ds_read_b128 v[98:101], v155
	ds_read_b128 v[102:105], v155 offset:64
	s_mov_b32 s16, 0xf149f2ca
	v_lshlrev_b32_e32 v186, 16, v29
	v_and_b32_e32 v187, 0xffff0000, v29
	v_pk_mul_f32 v[188:189], v[186:187], v[186:187]
	s_waitcnt lgkmcnt(1)
	v_mfma_f32_16x16x32_bf16 v[98:101], v[98:101], v[58:61], 0
	ds_read_b128 v[106:109], v155 offset:4416
	ds_read_b128 v[110:113], v155 offset:8768
	ds_read_b128 v[158:161], v155 offset:13120
	s_waitcnt lgkmcnt(3)
	v_mfma_f32_16x16x32_bf16 v[98:101], v[102:105], v[66:69], v[98:101]
	ds_read_b128 v[102:105], v155 offset:128
	s_waitcnt lgkmcnt(0)
	v_mfma_f32_16x16x32_bf16 v[98:101], v[102:105], v[70:73], v[98:101]
	ds_read_b128 v[102:105], v155 offset:192
	s_waitcnt lgkmcnt(0)
	v_mfma_f32_16x16x32_bf16 v[98:101], v[102:105], v[74:77], v[98:101]
	ds_read_b128 v[102:105], v155 offset:4352
	s_nop 6
	v_max3_f32 v146, v98, s16, v99
	v_max3_f32 v146, v146, v100, v101
	s_mov_b32 s16, 0x800000
	s_waitcnt lgkmcnt(0)
	v_mfma_f32_16x16x32_bf16 v[102:105], v[102:105], v[58:61], 0
	v_mfma_f32_16x16x32_bf16 v[102:105], v[106:109], v[66:69], v[102:105]
	ds_read_b128 v[106:109], v155 offset:4480
	s_waitcnt lgkmcnt(0)
	v_mfma_f32_16x16x32_bf16 v[102:105], v[106:109], v[70:73], v[102:105]
	ds_read_b128 v[106:109], v155 offset:4544
	s_waitcnt lgkmcnt(0)
	v_mfma_f32_16x16x32_bf16 v[102:105], v[106:109], v[74:77], v[102:105]
	ds_read_b128 v[106:109], v155 offset:8704
	s_nop 6
	v_max3_f32 v146, v146, v102, v103
	s_waitcnt lgkmcnt(0)
	v_mfma_f32_16x16x32_bf16 v[106:109], v[106:109], v[58:61], 0
	v_max3_f32 v146, v146, v104, v105
	v_mfma_f32_16x16x32_bf16 v[106:109], v[110:113], v[66:69], v[106:109]
	ds_read_b128 v[110:113], v155 offset:8832
	s_waitcnt lgkmcnt(0)
	v_mfma_f32_16x16x32_bf16 v[106:109], v[110:113], v[70:73], v[106:109]
	ds_read_b128 v[110:113], v155 offset:8896
	s_waitcnt lgkmcnt(0)
	v_mfma_f32_16x16x32_bf16 v[106:109], v[110:113], v[74:77], v[106:109]
	ds_read_b128 v[110:113], v155 offset:13056
	s_nop 6
	v_max3_f32 v146, v146, v106, v107
	s_waitcnt lgkmcnt(0)
	v_mfma_f32_16x16x32_bf16 v[110:113], v[110:113], v[58:61], 0
	v_max3_f32 v146, v146, v108, v109
	v_mfma_f32_16x16x32_bf16 v[110:113], v[158:161], v[66:69], v[110:113]
	ds_read_b128 v[158:161], v155 offset:13184
	s_waitcnt lgkmcnt(0)
	v_mfma_f32_16x16x32_bf16 v[110:113], v[158:161], v[70:73], v[110:113]
	ds_read_b128 v[158:161], v155 offset:13248
	s_waitcnt lgkmcnt(0)
	v_mfma_f32_16x16x32_bf16 v[110:113], v[158:161], v[74:77], v[110:113]
	s_nop 7
	v_max3_f32 v146, v146, v110, v111
	v_max3_f32 v146, v146, v112, v113
	ds_bpermute_b32 v158, v1, v146
	s_waitcnt lgkmcnt(0)
	v_max_f32_e32 v158, v158, v158
	v_max_f32_e32 v146, v146, v158
	ds_bpermute_b32 v158, v125, v146
	s_waitcnt lgkmcnt(0)
	v_max3_f32 v171, v157, v146, v158
	v_sub_f32_e32 v98, v98, v171
	v_sub_f32_e32 v146, v157, v171
	v_exp_f32_e32 v157, v98
	v_sub_f32_e32 v98, v99, v171
	v_exp_f32_e32 v172, v98
	v_sub_f32_e32 v98, v100, v171
	v_exp_f32_e32 v173, v98
	v_sub_f32_e32 v98, v101, v171
	v_exp_f32_e32 v169, v98
	v_sub_f32_e32 v98, v102, v171
	v_exp_f32_e32 v170, v98
	v_sub_f32_e32 v98, v103, v171
	v_exp_f32_e32 v168, v98
	v_sub_f32_e32 v98, v104, v171
	v_exp_f32_e32 v167, v98
	v_sub_f32_e32 v98, v105, v171
	v_exp_f32_e32 v166, v98
	v_sub_f32_e32 v98, v106, v171
	v_exp_f32_e32 v165, v98
	v_sub_f32_e32 v98, v107, v171
	v_exp_f32_e32 v164, v98
	v_sub_f32_e32 v98, v108, v171
	v_exp_f32_e32 v163, v98
	v_sub_f32_e32 v98, v109, v171
	v_exp_f32_e32 v161, v98
	v_sub_f32_e32 v98, v110, v171
	v_exp_f32_e32 v146, v146
	v_exp_f32_e32 v162, v98
	v_sub_f32_e32 v98, v111, v171
	v_exp_f32_e32 v160, v98
	v_sub_f32_e32 v98, v112, v171
	v_exp_f32_e32 v158, v98
	v_sub_f32_e32 v98, v113, v171
	v_exp_f32_e32 v159, v98
	v_pk_mul_f32 v[98:99], v[78:79], v[146:147] op_sel_hi:[1,0]
	v_add_u32_e32 v78, 0x4000, v152
	v_pk_mul_f32 v[108:109], v[96:97], v[146:147] op_sel_hi:[1,0]
	v_pk_mul_f32 v[106:107], v[94:95], v[146:147] op_sel_hi:[1,0]
	v_pk_mul_f32 v[96:97], v[64:65], v[146:147] op_sel_hi:[1,0]
	v_pk_mul_f32 v[94:95], v[62:63], v[146:147] op_sel_hi:[1,0]
	v_cvt_pk_bf16_f32 v178, v157, v172
	v_cvt_pk_bf16_f32 v179, v173, v169
	v_cvt_pk_bf16_f32 v180, v170, v168
	v_cvt_pk_bf16_f32 v181, v167, v166
	v_cvt_pk_bf16_f32 v182, v165, v164
	v_cvt_pk_bf16_f32 v183, v163, v161
	v_cvt_pk_bf16_f32 v184, v162, v160
	v_cvt_pk_bf16_f32 v185, v158, v159
	ds_read2_b64 v[62:65], v78 offset0:128 offset1:132
	v_pk_mul_f32 v[100:101], v[80:81], v[146:147] op_sel_hi:[1,0]
	ds_read2_b64 v[78:81], v78 offset0:136 offset1:140
	s_waitcnt lgkmcnt(1)
	v_mfma_f32_16x16x32_bf16 v[62:65], v[62:65], v[178:181], v[106:109]
	v_mul_f32_e64 v112, v92, v146
	v_mul_f32_e64 v113, v93, v146
	v_pk_mul_f32 v[110:111], v[90:91], v[146:147] op_sel_hi:[1,0]
	v_pk_mul_f32 v[176:177], v[88:89], v[146:147] op_sel_hi:[1,0]
	s_waitcnt lgkmcnt(0)
	v_mfma_f32_16x16x32_bf16 v[90:93], v[78:81], v[182:185], v[62:65]
	v_add_u32_e32 v78, 0x4800, v152
	v_pk_mul_f32 v[174:175], v[86:87], v[146:147] op_sel_hi:[1,0]
	v_pk_mul_f32 v[104:105], v[84:85], v[146:147] op_sel_hi:[1,0]
	ds_read2_b64 v[62:65], v78 offset0:160 offset1:164
	ds_read2_b64 v[78:81], v78 offset0:168 offset1:172
	s_waitcnt lgkmcnt(1)
	v_mfma_f32_16x16x32_bf16 v[62:65], v[62:65], v[178:181], v[110:113]
	v_mul_f32_e64 v102, v82, v146
	v_mul_f32_e64 v103, v83, v146
	v_pk_mul_f32 v[56:57], v[56:57], v[146:147] op_sel_hi:[1,0]
	v_pk_mul_f32 v[54:55], v[54:55], v[146:147] op_sel_hi:[1,0]
	s_waitcnt lgkmcnt(0)
	v_mfma_f32_16x16x32_bf16 v[86:89], v[78:81], v[182:185], v[62:65]
	v_add_u32_e32 v78, 0x5000, v152
	v_pk_mul_f32 v[52:53], v[52:53], v[146:147] op_sel_hi:[1,0]
	v_pk_mul_f32 v[50:51], v[50:51], v[146:147] op_sel_hi:[1,0]
	ds_read2_b64 v[62:65], v78 offset0:192 offset1:196
	ds_read2_b64 v[78:81], v78 offset0:200 offset1:204
	s_waitcnt lgkmcnt(1)
	v_mfma_f32_16x16x32_bf16 v[62:65], v[62:65], v[178:181], v[174:177]
	v_lshlrev_b32_e32 v106, 16, v32
	v_and_b32_e32 v107, 0xffff0000, v32
	v_pk_mul_f32 v[108:109], v[106:107], v[106:107]
	s_waitcnt lgkmcnt(0)
	v_mfma_f32_16x16x32_bf16 v[82:85], v[78:81], v[182:185], v[62:65]
	v_add_u32_e32 v78, 0x5800, v152
	v_lshlrev_b32_e32 v174, 16, v33
	v_and_b32_e32 v175, 0xffff0000, v33
	ds_read2_b64 v[62:65], v78 offset0:224 offset1:228
	ds_read2_b64 v[78:81], v78 offset0:232 offset1:236
	s_waitcnt lgkmcnt(1)
	v_mfma_f32_16x16x32_bf16 v[62:65], v[62:65], v[178:181], v[102:105]
	s_nop 2
	v_add_u32_e32 v102, 0x6800, v152
	v_and_b32_e32 v103, 0xffff0000, v31
	v_pk_mul_f32 v[110:111], v[174:175], v[174:175]
	s_waitcnt lgkmcnt(0)
	v_mfma_f32_16x16x32_bf16 v[78:81], v[78:81], v[182:185], v[62:65]
	v_lshlrev_b32_e32 v176, 16, v26
	v_and_b32_e32 v177, 0xffff0000, v26
	v_pk_mul_f32 v[112:113], v[176:177], v[176:177]
	ds_read2_b64 v[62:65], v102 offset1:4
	s_waitcnt lgkmcnt(0)
	v_mfma_f32_16x16x32_bf16 v[62:65], v[62:65], v[178:181], v[98:101]
	s_nop 2
	ds_read2_b64 v[98:101], v102 offset0:8 offset1:12
	v_add_u32_e32 v102, 0x7000, v152
	s_waitcnt lgkmcnt(0)
	v_mfma_f32_16x16x32_bf16 v[62:65], v[98:101], v[182:185], v[62:65]
	ds_read2_b64 v[98:101], v102 offset0:32 offset1:36
	s_waitcnt lgkmcnt(0)
	v_mfma_f32_16x16x32_bf16 v[94:97], v[98:101], v[178:181], v[94:97]
	ds_read2_b64 v[98:101], v102 offset0:40 offset1:44
	v_add_u32_e32 v102, 0x7800, v152
	s_waitcnt lgkmcnt(0)
	v_mfma_f32_16x16x32_bf16 v[98:101], v[98:101], v[182:185], v[94:97]
	s_nop 3
	ds_read2_b64 v[94:97], v102 offset0:64 offset1:68
	s_waitcnt lgkmcnt(0)
	v_mfma_f32_16x16x32_bf16 v[54:57], v[94:97], v[178:181], v[54:57]
	ds_read2_b64 v[94:97], v102 offset0:72 offset1:76
	v_add_u32_e32 v102, 0x8000, v152
	s_waitcnt lgkmcnt(0)
	v_mfma_f32_16x16x32_bf16 v[54:57], v[94:97], v[182:185], v[54:57]
	ds_read2_b64 v[94:97], v102 offset0:96 offset1:100
	s_waitcnt lgkmcnt(0)
	v_mfma_f32_16x16x32_bf16 v[50:53], v[94:97], v[178:181], v[50:53]
	ds_read2_b64 v[94:97], v102 offset0:104 offset1:108
	v_lshlrev_b32_e32 v102, 16, v31
	v_pk_mul_f32 v[104:105], v[102:103], v[102:103]
	s_waitcnt lgkmcnt(0)
	v_mfma_f32_16x16x32_bf16 v[50:53], v[94:97], v[182:185], v[50:53]
	v_lshlrev_b32_e32 v94, 16, v30
	v_and_b32_e32 v95, 0xffff0000, v30
	v_pk_mul_f32 v[96:97], v[94:95], v[94:95]
	v_lshlrev_b32_e32 v178, 16, v27
	v_add_f32_e32 v96, v96, v97
	v_add_f32_e32 v96, v104, v96
	v_add_f32_e32 v96, v105, v96
	v_add_f32_e32 v96, v108, v96
	v_add_f32_e32 v96, v109, v96
	v_add_f32_e32 v96, v110, v96
	v_add_f32_e32 v96, v111, v96
	v_and_b32_e32 v179, 0xffff0000, v27
	v_add_f32_e32 v96, v112, v96
	v_pk_mul_f32 v[180:181], v[178:179], v[178:179]
	v_add_f32_e32 v96, v113, v96
	v_lshlrev_b32_e32 v182, 16, v28
	v_and_b32_e32 v183, 0xffff0000, v28
	v_add_f32_e32 v96, v180, v96
	v_pk_mul_f32 v[184:185], v[182:183], v[182:183]
	v_add_f32_e32 v96, v181, v96
	v_add_f32_e32 v96, v184, v96
	v_add_f32_e32 v96, v185, v96
	v_add_f32_e32 v96, v188, v96
	v_add_f32_e32 v96, v189, v96
	s_nop 1
	v_add_f32_dpp v96, v96, v96 quad_perm:[1,0,3,2] row_mask:0xf bank_mask:0xf
	s_nop 1
	v_add_f32_dpp v96, v96, v96 quad_perm:[2,3,0,1] row_mask:0xf bank_mask:0xf
	s_nop 1
	v_add_f32_dpp v96, v96, v96 row_half_mirror row_mask:0xf bank_mask:0xf
	s_nop 0
	v_fmamk_f32 v96, v96, 0x3c000000, v221
	v_cmp_gt_f32_e32 vcc, s16, v96
	v_mul_f32_e32 v97, 0x4b800000, v96
	s_nop 0
	v_cndmask_b32_e32 v96, v96, v97, vcc
	v_rsq_f32_e32 v96, v96
	s_nop 0
	v_mul_f32_e32 v97, 0x45800000, v96
	v_cndmask_b32_e32 v96, v96, v97, vcc
	v_pk_mul_f32 v[94:95], v[96:97], v[94:95] op_sel_hi:[0,1]
	v_pk_mul_f32 v[110:111], v[14:15], v[94:95]
	v_pk_mul_f32 v[94:95], v[96:97], v[102:103] op_sel_hi:[0,1]
	v_pk_mul_f32 v[112:113], v[16:17], v[94:95]
	v_pk_mul_f32 v[94:95], v[96:97], v[106:107] op_sel_hi:[0,1]
	v_pk_mul_f32 v[106:107], v[10:11], v[94:95]
	v_pk_mul_f32 v[94:95], v[96:97], v[174:175] op_sel_hi:[0,1]
	v_pk_mul_f32 v[108:109], v[12:13], v[94:95]
	v_pk_mul_f32 v[94:95], v[96:97], v[176:177] op_sel_hi:[0,1]
	v_pk_mul_f32 v[102:103], v[6:7], v[94:95]
	v_pk_mul_f32 v[94:95], v[96:97], v[178:179] op_sel_hi:[0,1]
	v_pk_mul_f32 v[104:105], v[8:9], v[94:95]
	v_pk_mul_f32 v[94:95], v[96:97], v[182:183] op_sel_hi:[0,1]
	v_pk_mul_f32 v[96:97], v[96:97], v[186:187] op_sel_hi:[0,1]
	v_pk_mul_f32 v[94:95], v[2:3], v[94:95]
	v_pk_mul_f32 v[96:97], v[4:5], v[96:97]
	s_and_b64 vcc, exec, s[38:39]
	s_cbranch_vccnz .LBB0_455
	v_add_u32_e32 v174, s5, v154
	v_ashrrev_i32_e32 v175, 31, v174
	v_lshlrev_b64 v[174:175], 12, v[174:175]
	v_lshl_add_u64 v[174:175], v[144:145], 0, v[174:175]
	global_store_dwordx4 v[174:175], v[110:113], off
	global_store_dwordx4 v[174:175], v[106:109], off offset:16
	global_store_dwordx4 v[174:175], v[102:105], off offset:32
	global_store_dwordx4 v[174:175], v[94:97], off offset:48

.LBB0_562:
	s_andn2_b64 vcc, exec, s[0:1]
	s_cbranch_vccnz .LBB0_564
	s_waitcnt vmcnt(2)
	v_and_b32_e32 v113, 0xffff0000, v48
	v_lshlrev_b32_e32 v114, 16, v48
	v_mul_f32_e32 v102, v113, v113
	v_lshlrev_b32_e32 v112, 16, v49
	v_fmac_f32_e32 v102, v114, v114
	v_and_b32_e32 v111, 0xffff0000, v49
	v_fmac_f32_e32 v102, v112, v112
	v_lshlrev_b32_e32 v110, 16, v50
	v_fmac_f32_e32 v102, v111, v111
	v_and_b32_e32 v109, 0xffff0000, v50
	v_fmac_f32_e32 v102, v110, v110
	v_lshlrev_b32_e32 v108, 16, v51
	v_fmac_f32_e32 v102, v109, v109
	v_and_b32_e32 v1, 0xffff0000, v51
	v_fmac_f32_e32 v102, v108, v108
	v_and_b32_e32 v2, 0xffff0000, v44
	v_lshlrev_b32_e32 v3, 16, v44
	v_fmac_f32_e32 v102, v1, v1
	v_pk_mul_f32 v[100:101], v[2:3], v[2:3]
	s_mov_b32 s0, 0x800000
	v_add_f32_e32 v101, v101, v102
	v_add_f32_e32 v104, v100, v101
	v_and_b32_e32 v100, 0xffff0000, v45
	v_lshlrev_b32_e32 v101, 16, v45
	v_pk_mul_f32 v[102:103], v[100:101], v[100:101]
	s_nop 0
	v_add_f32_e32 v103, v103, v104
	v_add_f32_e32 v106, v102, v103
	v_and_b32_e32 v102, 0xffff0000, v46
	v_lshlrev_b32_e32 v103, 16, v46
	v_pk_mul_f32 v[104:105], v[102:103], v[102:103]
	s_nop 0
	v_add_f32_e32 v105, v105, v106
	v_add_f32_e32 v115, v104, v105
	v_and_b32_e32 v104, 0xffff0000, v47
	v_lshlrev_b32_e32 v105, 16, v47
	v_pk_mul_f32 v[106:107], v[104:105], v[104:105]
	s_nop 0
	v_add_f32_e32 v107, v107, v115
	v_add_f32_e32 v106, v106, v107
	s_nop 1
	v_add_f32_dpp v106, v106, v106 quad_perm:[1,0,3,2] row_mask:0xf bank_mask:0xf
	s_nop 1
	v_add_f32_dpp v106, v106, v106 quad_perm:[2,3,0,1] row_mask:0xf bank_mask:0xf
	s_nop 1
	v_add_f32_dpp v106, v106, v106 row_half_mirror row_mask:0xf bank_mask:0xf
	s_nop 0
	v_fmamk_f32 v106, v106, 0x3c000000, v221
	v_mul_f32_e32 v107, 0x4b800000, v106
	v_cmp_gt_f32_e32 vcc, s0, v106
	s_nop 1
	v_cndmask_b32_e32 v106, v106, v107, vcc
	v_rsq_f32_e32 v106, v106
	s_nop 0
	v_mul_f32_e32 v107, 0x45800000, v106
	v_cndmask_b32_e32 v106, v106, v107, vcc
	v_mul_f32_e32 v100, v106, v100
	v_mul_f32_e32 v115, v31, v100
	v_mul_f32_e32 v100, v106, v103
	v_mul_f32_e32 v116, v24, v100
	v_mul_f32_e32 v100, v106, v102
	v_mul_f32_e32 v107, v106, v114
	v_mul_f32_e32 v117, v25, v100
	v_mul_f32_e32 v100, v106, v105
	v_mul_f32_e32 v107, v36, v107
	v_mul_f32_e32 v113, v106, v113
	v_mul_f32_e32 v112, v106, v112
	v_mul_f32_e32 v111, v106, v111
	v_mul_f32_e32 v110, v106, v110
	v_mul_f32_e32 v109, v106, v109
	v_mul_f32_e32 v108, v106, v108
	v_mul_f32_e32 v1, v106, v1
	v_mul_f32_e32 v3, v106, v3
	v_mul_f32_e32 v2, v106, v2
	v_mul_f32_e32 v101, v106, v101
	v_mul_f32_e32 v118, v26, v100
	v_mul_f32_e32 v100, v106, v104
	v_mul_f32_e32 v113, v37, v113
	v_mul_f32_e32 v112, v38, v112
	v_mul_f32_e32 v111, v39, v111
	v_mul_f32_e32 v110, v32, v110
	v_mul_f32_e32 v109, v33, v109
	v_mul_f32_e32 v108, v34, v108
	v_mul_f32_e32 v1, v35, v1
	v_mul_f32_e32 v3, v28, v3
	v_mul_f32_e32 v2, v29, v2
	v_mul_f32_e32 v114, v30, v101
	v_mul_f32_e32 v119, v27, v100
	v_cvt_pk_bf16_f32 v100, v107, v113
	v_cvt_pk_bf16_f32 v101, v112, v111
	v_cvt_pk_bf16_f32 v102, v110, v109
	v_cvt_pk_bf16_f32 v103, v108, v1
	v_cvt_pk_bf16_f32 v104, v3, v2
	v_cvt_pk_bf16_f32 v105, v114, v115
	v_cvt_pk_bf16_f32 v106, v116, v117
	v_cvt_pk_bf16_f32 v107, v118, v119

.LBB0_574:
	v_add_u32_e32 v1, v166, v168
	v_readfirstlane_b32 s16, v180
	v_mov_b64_e32 v[114:115], 0
	v_mov_b64_e32 v[116:117], 0
	v_mov_b64_e32 v[104:105], 0
	v_mov_b64_e32 v[106:107], 0
	v_mov_b64_e32 v[108:109], 0
	v_mov_b64_e32 v[110:111], 0
	v_mov_b64_e32 v[100:101], 0
	v_mov_b64_e32 v[102:103], 0
	s_bitcmp1_b32 s16, 0
	s_cbranch_scc0 .Lal_q0_a
	ds_read_b128 v[182:185], v1 offset:0
	ds_read_b128 v[186:189], v1 offset:64
	ds_read_b128 v[190:193], v1 offset:128
	ds_read_b128 v[204:207], v1 offset:192
	s_waitcnt lgkmcnt(3)
	v_mfma_f32_16x16x32_bf16 v[114:117], v[182:185], v[80:83], 0
	s_waitcnt lgkmcnt(2)
	v_mfma_f32_16x16x32_bf16 v[114:117], v[186:189], v[84:87], v[114:117]
	s_waitcnt lgkmcnt(1)
	v_mfma_f32_16x16x32_bf16 v[114:117], v[190:193], v[88:91], v[114:117]
	s_waitcnt lgkmcnt(0)
	v_mfma_f32_16x16x32_bf16 v[114:117], v[204:207], v[92:95], v[114:117]
.Lal_q0_a:
	s_bitcmp1_b32 s16, 1
	s_cbranch_scc0 .Lal_q1_a
	ds_read_b128 v[208:211], v1 offset:4352
	ds_read_b128 v[212:215], v1 offset:4416
	ds_read_b128 v[216:219], v1 offset:4480
	ds_read_b128 v[118:121], v1 offset:4544
	s_waitcnt lgkmcnt(3)
	v_mfma_f32_16x16x32_bf16 v[104:107], v[208:211], v[80:83], 0
	s_waitcnt lgkmcnt(2)
	v_mfma_f32_16x16x32_bf16 v[104:107], v[212:215], v[84:87], v[104:107]
	s_waitcnt lgkmcnt(1)
	v_mfma_f32_16x16x32_bf16 v[104:107], v[216:219], v[88:91], v[104:107]
	s_waitcnt lgkmcnt(0)
	v_mfma_f32_16x16x32_bf16 v[104:107], v[118:121], v[92:95], v[104:107]
.Lal_q1_a:
	s_bitcmp1_b32 s16, 2
	s_cbranch_scc0 .Lal_q2_a
	ds_read_b128 v[182:185], v1 offset:8704
	ds_read_b128 v[186:189], v1 offset:8768
	ds_read_b128 v[190:193], v1 offset:8832
	ds_read_b128 v[204:207], v1 offset:8896
	s_waitcnt lgkmcnt(3)
	v_mfma_f32_16x16x32_bf16 v[108:111], v[182:185], v[80:83], 0
	s_waitcnt lgkmcnt(2)
	v_mfma_f32_16x16x32_bf16 v[108:111], v[186:189], v[84:87], v[108:111]
	s_waitcnt lgkmcnt(1)
	v_mfma_f32_16x16x32_bf16 v[108:111], v[190:193], v[88:91], v[108:111]
	s_waitcnt lgkmcnt(0)
	v_mfma_f32_16x16x32_bf16 v[108:111], v[204:207], v[92:95], v[108:111]
.Lal_q2_a:
	s_bitcmp1_b32 s16, 3
	s_cbranch_scc0 .Lal_q3_a
	ds_read_b128 v[208:211], v1 offset:13056
	ds_read_b128 v[212:215], v1 offset:13120
	ds_read_b128 v[216:219], v1 offset:13184
	ds_read_b128 v[118:121], v1 offset:13248
	s_waitcnt lgkmcnt(3)
	v_mfma_f32_16x16x32_bf16 v[100:103], v[208:211], v[80:83], 0
	s_waitcnt lgkmcnt(2)
	v_mfma_f32_16x16x32_bf16 v[100:103], v[212:215], v[84:87], v[100:103]
	s_waitcnt lgkmcnt(1)
	v_mfma_f32_16x16x32_bf16 v[100:103], v[216:219], v[88:91], v[100:103]
	s_waitcnt lgkmcnt(0)
	v_mfma_f32_16x16x32_bf16 v[100:103], v[118:121], v[92:95], v[100:103]
.Lal_q3_a:
	s_and_b64 vcc, exec, s[0:1]
	s_cbranch_vccnz .Lal_nowin_a
	s_mov_b32 s17, 0x123a0
	v_add3_u32 v3, v178, v176, s17
	ds_read_b32 v122, v3
	ds_read_b32 v123, v3 offset:4
	ds_read_b32 v124, v3 offset:8
	ds_read_b32 v125, v3 offset:12
	ds_read_b32 v126, v3 offset:64
	ds_read_b32 v127, v3 offset:68
	ds_read_b32 v128, v3 offset:72
	ds_read_b32 v129, v3 offset:76
	ds_read_b32 v182, v3 offset:128
	ds_read_b32 v183, v3 offset:132
	ds_read_b32 v184, v3 offset:136
	ds_read_b32 v185, v3 offset:140
	ds_read_b32 v186, v3 offset:192
	ds_read_b32 v187, v3 offset:196
	ds_read_b32 v188, v3 offset:200
	ds_read_b32 v189, v3 offset:204
	v_mov_b32_e32 v2, 0xf149f2ca
	s_waitcnt lgkmcnt(12)
	v_add_f32_e32 v122, v114, v122
	v_add_f32_e32 v123, v115, v123
	v_add_f32_e32 v124, v116, v124
	v_add_f32_e32 v125, v117, v125
	v_cndmask_b32_e64 v114, v2, v122, s[38:39]
	v_cndmask_b32_e64 v115, v2, v123, s[40:41]
	v_cndmask_b32_e64 v116, v2, v124, s[42:43]
	v_cndmask_b32_e64 v117, v2, v125, s[44:45]
	s_waitcnt lgkmcnt(8)
	v_add_f32_e32 v126, v104, v126
	v_add_f32_e32 v127, v105, v127
	v_add_f32_e32 v128, v106, v128
	v_add_f32_e32 v129, v107, v129
	v_cndmask_b32_e64 v104, v2, v126, s[28:29]
	v_cndmask_b32_e64 v105, v2, v127, s[56:57]
	v_cndmask_b32_e64 v106, v2, v128, s[58:59]
	v_cndmask_b32_e64 v107, v2, v129, s[60:61]
	s_waitcnt lgkmcnt(4)
	v_add_f32_e32 v182, v108, v182
	v_add_f32_e32 v183, v109, v183
	v_add_f32_e32 v184, v110, v184
	v_add_f32_e32 v185, v111, v185
	v_cndmask_b32_e64 v108, v2, v182, s[36:37]
	v_cndmask_b32_e64 v109, v2, v183, s[62:63]
	v_cndmask_b32_e64 v110, v2, v184, s[64:65]
	v_cndmask_b32_e64 v111, v2, v185, s[2:3]
	s_waitcnt lgkmcnt(0)
	v_add_f32_e32 v186, v100, v186
	v_add_f32_e32 v187, v101, v187
	v_add_f32_e32 v188, v102, v188
	v_add_f32_e32 v189, v103, v189
	v_cndmask_b32_e64 v100, v2, v186, s[46:47]
	v_cndmask_b32_e64 v101, v2, v187, s[48:49]
	v_cndmask_b32_e64 v102, v2, v188, s[50:51]
	v_cndmask_b32_e64 v103, v2, v189, s[52:53]
	s_branch .Lal_sm_a
.Lal_nowin_a:
	s_nop 7
.Lal_sm_a:
	s_mov_b32 s0, 0xf149f2ca
	v_max3_f32 v1, v114, s0, v115
	v_max3_f32 v1, v1, v116, v117
	v_max3_f32 v1, v1, v104, v105
	v_max3_f32 v1, v1, v106, v107
	v_max3_f32 v1, v1, v108, v109
	v_max3_f32 v1, v1, v110, v111
	v_max3_f32 v1, v1, v100, v101
	v_max3_f32 v1, v1, v102, v103
	ds_bpermute_b32 v2, v159, v1
	s_waitcnt lgkmcnt(0)
	v_max_f32_e32 v2, v2, v2
	v_max_f32_e32 v1, v1, v2
	ds_bpermute_b32 v2, v158, v1
	s_waitcnt lgkmcnt(0)
	v_max3_f32 v1, v179, v1, v2
	v_sub_f32_e32 v3, v114, v1
	v_exp_f32_e32 v112, v3
	v_sub_f32_e32 v3, v105, v1
	v_sub_f32_e32 v113, v115, v1
	v_sub_f32_e32 v115, v117, v1
	v_exp_f32_e32 v117, v3
	v_sub_f32_e32 v3, v106, v1
	v_exp_f32_e32 v118, v3
	v_sub_f32_e32 v3, v107, v1
	v_exp_f32_e32 v119, v3
	v_sub_f32_e32 v3, v108, v1
	v_exp_f32_e32 v108, v3
	v_sub_f32_e32 v3, v109, v1
	v_exp_f32_e32 v109, v3
	v_sub_f32_e32 v3, v110, v1
	v_exp_f32_e32 v110, v3
	v_sub_f32_e32 v3, v111, v1
	v_exp_f32_e32 v111, v3
	v_sub_f32_e32 v3, v100, v1
	v_sub_f32_e32 v2, v179, v1
	v_exp_f32_e32 v120, v3
	v_sub_f32_e32 v3, v101, v1
	v_exp_f32_e32 v121, v3
	v_sub_f32_e32 v3, v102, v1
	v_exp_f32_e32 v2, v2
	v_sub_f32_e32 v114, v116, v1
	v_sub_f32_e32 v104, v104, v1
	v_exp_f32_e32 v122, v3
	v_sub_f32_e32 v3, v103, v1
	v_exp_f32_e32 v113, v113
	v_exp_f32_e32 v114, v114
	v_exp_f32_e32 v115, v115
	v_exp_f32_e32 v116, v104
	v_exp_f32_e32 v123, v3
	v_pk_mul_f32 v[98:99], v[98:99], v[2:3] op_sel_hi:[1,0]
	v_pk_mul_f32 v[96:97], v[96:97], v[2:3] op_sel_hi:[1,0]
	v_cvt_pk_bf16_f32 v104, v112, v113
	v_cvt_pk_bf16_f32 v105, v114, v115
	v_cvt_pk_bf16_f32 v106, v116, v117
	v_cvt_pk_bf16_f32 v107, v118, v119
	v_cvt_pk_bf16_f32 v100, v108, v109
	v_cvt_pk_bf16_f32 v101, v110, v111
	v_cvt_pk_bf16_f32 v102, v120, v121
	v_cvt_pk_bf16_f32 v103, v122, v123
	v_add_f32_e32 v3, 0, v112
	v_add_f32_e32 v3, v113, v3
	v_add_f32_e32 v3, v114, v3
	v_add_f32_e32 v3, v115, v3
	v_add_f32_e32 v3, v116, v3
	v_add_f32_e32 v3, v117, v3
	v_add_f32_e32 v3, v118, v3
	v_add_f32_e32 v3, v119, v3
	v_add_f32_e32 v3, v108, v3
	v_add_f32_e32 v3, v109, v3
	v_add_f32_e32 v3, v110, v3
	v_add_f32_e32 v3, v111, v3
	v_add_f32_e32 v3, v120, v3
	v_add_f32_e32 v3, v121, v3
	v_add_f32_e32 v3, v122, v3
	v_add_f32_e32 v3, v123, v3
	v_fmac_f32_e32 v3, v171, v2
	v_mov_b32_e32 v179, v1
	v_mov_b32_e32 v171, v3
	v_pk_mul_f32 v[78:79], v[78:79], v[2:3] op_sel_hi:[1,0]
	v_pk_mul_f32 v[76:77], v[76:77], v[2:3] op_sel_hi:[1,0]
	v_pk_mul_f32 v[42:43], v[42:43], v[2:3] op_sel_hi:[1,0]
	v_pk_mul_f32 v[40:41], v[40:41], v[2:3] op_sel_hi:[1,0]
	v_pk_mul_f32 v[22:23], v[22:23], v[2:3] op_sel_hi:[1,0]
	v_pk_mul_f32 v[20:21], v[20:21], v[2:3] op_sel_hi:[1,0]
	v_pk_mul_f32 v[18:19], v[18:19], v[2:3] op_sel_hi:[1,0]
	v_pk_mul_f32 v[16:17], v[16:17], v[2:3] op_sel_hi:[1,0]
	v_pk_mul_f32 v[14:15], v[14:15], v[2:3] op_sel_hi:[1,0]
	v_pk_mul_f32 v[12:13], v[12:13], v[2:3] op_sel_hi:[1,0]
	v_pk_mul_f32 v[10:11], v[10:11], v[2:3] op_sel_hi:[1,0]
	v_pk_mul_f32 v[8:9], v[8:9], v[2:3] op_sel_hi:[1,0]
	v_pk_mul_f32 v[6:7], v[6:7], v[2:3] op_sel_hi:[1,0]
	v_pk_mul_f32 v[4:5], v[4:5], v[2:3] op_sel_hi:[1,0]
	v_add_u32_e32 v1, 17408, v169
	s_and_b32 s17, s16, 3
	s_cmp_eq_u32 s17, 0
	s_cbranch_scc1 .Lal_pv1only_a
	s_and_b32 s17, s16, 12
	s_cmp_eq_u32 s17, 0
	s_cbranch_scc1 .Lal_pv0only_a
	v_add_u32_e32 v3, 0, v1
	ds_read2_b64 v[182:185], v3 offset0:0 offset1:4
	v_add_u32_e32 v3, 2304, v1
	ds_read2_b64 v[186:189], v3 offset0:0 offset1:4
	v_add_u32_e32 v3, 4608, v1
	ds_read2_b64 v[190:193], v3 offset0:0 offset1:4
	v_add_u32_e32 v3, 6912, v1
	ds_read2_b64 v[204:207], v3 offset0:0 offset1:4
	v_add_u32_e32 v3, 9216, v1
	ds_read2_b64 v[208:211], v3 offset0:0 offset1:4
	v_add_u32_e32 v3, 11520, v1
	ds_read2_b64 v[212:215], v3 offset0:0 offset1:4
	v_add_u32_e32 v3, 13824, v1
	ds_read2_b64 v[216:219], v3 offset0:0 offset1:4
	v_add_u32_e32 v3, 16128, v1
	ds_read2_b64 v[118:121], v3 offset0:0 offset1:4
	s_waitcnt lgkmcnt(7)
	v_mfma_f32_16x16x32_bf16 v[96:99], v[182:185], v[104:107], v[96:99]
	v_add_u32_e32 v3, 0, v1
	ds_read2_b64 v[182:185], v3 offset0:8 offset1:12
	s_waitcnt lgkmcnt(7)
	v_mfma_f32_16x16x32_bf16 v[76:79], v[186:189], v[104:107], v[76:79]
	v_add_u32_e32 v3, 2304, v1
	ds_read2_b64 v[186:189], v3 offset0:8 offset1:12
	s_waitcnt lgkmcnt(7)
	v_mfma_f32_16x16x32_bf16 v[40:43], v[190:193], v[104:107], v[40:43]
	v_add_u32_e32 v3, 4608, v1
	ds_read2_b64 v[190:193], v3 offset0:8 offset1:12
	s_waitcnt lgkmcnt(7)
	v_mfma_f32_16x16x32_bf16 v[20:23], v[204:207], v[104:107], v[20:23]
	v_add_u32_e32 v3, 6912, v1
	ds_read2_b64 v[204:207], v3 offset0:8 offset1:12
	s_waitcnt lgkmcnt(7)
	v_mfma_f32_16x16x32_bf16 v[16:19], v[208:211], v[104:107], v[16:19]
	v_add_u32_e32 v3, 9216, v1
	ds_read2_b64 v[208:211], v3 offset0:8 offset1:12
	s_waitcnt lgkmcnt(7)
	v_mfma_f32_16x16x32_bf16 v[12:15], v[212:215], v[104:107], v[12:15]
	v_add_u32_e32 v3, 11520, v1
	ds_read2_b64 v[212:215], v3 offset0:8 offset1:12
	s_waitcnt lgkmcnt(7)
	v_mfma_f32_16x16x32_bf16 v[8:11], v[216:219], v[104:107], v[8:11]
	v_add_u32_e32 v3, 13824, v1
	ds_read2_b64 v[216:219], v3 offset0:8 offset1:12
	s_waitcnt lgkmcnt(7)
	v_mfma_f32_16x16x32_bf16 v[4:7], v[118:121], v[104:107], v[4:7]
	v_add_u32_e32 v3, 16128, v1
	ds_read2_b64 v[118:121], v3 offset0:8 offset1:12
	s_waitcnt lgkmcnt(7)
	v_mfma_f32_16x16x32_bf16 v[96:99], v[182:185], v[100:103], v[96:99]
	s_waitcnt lgkmcnt(6)
	v_mfma_f32_16x16x32_bf16 v[76:79], v[186:189], v[100:103], v[76:79]
	s_waitcnt lgkmcnt(5)
	v_mfma_f32_16x16x32_bf16 v[40:43], v[190:193], v[100:103], v[40:43]
	s_waitcnt lgkmcnt(4)
	v_mfma_f32_16x16x32_bf16 v[20:23], v[204:207], v[100:103], v[20:23]
	s_waitcnt lgkmcnt(3)
	v_mfma_f32_16x16x32_bf16 v[16:19], v[208:211], v[100:103], v[16:19]
	s_waitcnt lgkmcnt(2)
	v_mfma_f32_16x16x32_bf16 v[12:15], v[212:215], v[100:103], v[12:15]
	s_waitcnt lgkmcnt(1)
	v_mfma_f32_16x16x32_bf16 v[8:11], v[216:219], v[100:103], v[8:11]
	s_waitcnt lgkmcnt(0)
	v_mfma_f32_16x16x32_bf16 v[4:7], v[118:121], v[100:103], v[4:7]
	s_branch .Lal_pvdone_a
.Lal_pv0only_a:
	v_add_u32_e32 v3, 0, v1
	ds_read2_b64 v[182:185], v3 offset0:0 offset1:4
	v_add_u32_e32 v3, 2304, v1
	ds_read2_b64 v[186:189], v3 offset0:0 offset1:4
	v_add_u32_e32 v3, 4608, v1
	ds_read2_b64 v[190:193], v3 offset0:0 offset1:4
	v_add_u32_e32 v3, 6912, v1
	ds_read2_b64 v[204:207], v3 offset0:0 offset1:4
	v_add_u32_e32 v3, 9216, v1
	ds_read2_b64 v[208:211], v3 offset0:0 offset1:4
	v_add_u32_e32 v3, 11520, v1
	ds_read2_b64 v[212:215], v3 offset0:0 offset1:4
	v_add_u32_e32 v3, 13824, v1
	ds_read2_b64 v[216:219], v3 offset0:0 offset1:4
	v_add_u32_e32 v3, 16128, v1
	ds_read2_b64 v[118:121], v3 offset0:0 offset1:4
	s_waitcnt lgkmcnt(7)
	v_mfma_f32_16x16x32_bf16 v[96:99], v[182:185], v[104:107], v[96:99]
	s_waitcnt lgkmcnt(6)
	v_mfma_f32_16x16x32_bf16 v[76:79], v[186:189], v[104:107], v[76:79]
	s_waitcnt lgkmcnt(5)
	v_mfma_f32_16x16x32_bf16 v[40:43], v[190:193], v[104:107], v[40:43]
	s_waitcnt lgkmcnt(4)
	v_mfma_f32_16x16x32_bf16 v[20:23], v[204:207], v[104:107], v[20:23]
	s_waitcnt lgkmcnt(3)
	v_mfma_f32_16x16x32_bf16 v[16:19], v[208:211], v[104:107], v[16:19]
	s_waitcnt lgkmcnt(2)
	v_mfma_f32_16x16x32_bf16 v[12:15], v[212:215], v[104:107], v[12:15]
	s_waitcnt lgkmcnt(1)
	v_mfma_f32_16x16x32_bf16 v[8:11], v[216:219], v[104:107], v[8:11]
	s_waitcnt lgkmcnt(0)
	v_mfma_f32_16x16x32_bf16 v[4:7], v[118:121], v[104:107], v[4:7]
	s_branch .Lal_pvdone_a
.Lal_pv1only_a:
	v_add_u32_e32 v3, 0, v1
	ds_read2_b64 v[182:185], v3 offset0:8 offset1:12
	v_add_u32_e32 v3, 2304, v1
	ds_read2_b64 v[186:189], v3 offset0:8 offset1:12
	v_add_u32_e32 v3, 4608, v1
	ds_read2_b64 v[190:193], v3 offset0:8 offset1:12
	v_add_u32_e32 v3, 6912, v1
	ds_read2_b64 v[204:207], v3 offset0:8 offset1:12
	v_add_u32_e32 v3, 9216, v1
	ds_read2_b64 v[208:211], v3 offset0:8 offset1:12
	v_add_u32_e32 v3, 11520, v1
	ds_read2_b64 v[212:215], v3 offset0:8 offset1:12
	v_add_u32_e32 v3, 13824, v1
	ds_read2_b64 v[216:219], v3 offset0:8 offset1:12
	v_add_u32_e32 v3, 16128, v1
	ds_read2_b64 v[118:121], v3 offset0:8 offset1:12
	s_waitcnt lgkmcnt(7)
	v_mfma_f32_16x16x32_bf16 v[96:99], v[182:185], v[100:103], v[96:99]
	s_waitcnt lgkmcnt(6)
	v_mfma_f32_16x16x32_bf16 v[76:79], v[186:189], v[100:103], v[76:79]
	s_waitcnt lgkmcnt(5)
	v_mfma_f32_16x16x32_bf16 v[40:43], v[190:193], v[100:103], v[40:43]
	s_waitcnt lgkmcnt(4)
	v_mfma_f32_16x16x32_bf16 v[20:23], v[204:207], v[100:103], v[20:23]
	s_waitcnt lgkmcnt(3)
	v_mfma_f32_16x16x32_bf16 v[16:19], v[208:211], v[100:103], v[16:19]
	s_waitcnt lgkmcnt(2)
	v_mfma_f32_16x16x32_bf16 v[12:15], v[212:215], v[100:103], v[12:15]
	s_waitcnt lgkmcnt(1)
	v_mfma_f32_16x16x32_bf16 v[8:11], v[216:219], v[100:103], v[8:11]
	s_waitcnt lgkmcnt(0)
	v_mfma_f32_16x16x32_bf16 v[4:7], v[118:121], v[100:103], v[4:7]
.Lal_pvdone_a:
	s_or_b64 exec, exec, s[4:5]
	s_add_i32 s0, s23, -2
	s_cmp_ge_i32 s0, s22
	s_cbranch_scc1 .LBB0_559
.LBB0_649:
	s_cmp_lt_i32 s0, s67
	s_cselect_b64 s[4:5], -1, 0
	s_cmp_ge_i32 s0, s67
	s_cselect_b64 s[16:17], -1, 0
	s_mov_b64 s[0:1], -1
	s_and_b64 vcc, exec, s[4:5]
	s_cbranch_vccnz .LBB0_651
	v_mov_b64_e32 v[106:107], v[62:63]
	v_mov_b64_e32 v[102:103], v[66:67]
	s_mov_b64 s[0:1], 0
	v_mov_b64_e32 v[104:105], v[60:61]
	v_mov_b64_e32 v[100:101], v[64:65]
.LBB0_651:
	s_andn2_b64 vcc, exec, s[0:1]
	s_cbranch_vccnz .LBB0_653
	v_and_b32_e32 v113, 0xffff0000, v64
	v_lshlrev_b32_e32 v114, 16, v64
	v_mul_f32_e32 v102, v113, v113
	v_lshlrev_b32_e32 v112, 16, v65
	v_fmac_f32_e32 v102, v114, v114
	v_and_b32_e32 v111, 0xffff0000, v65
	v_fmac_f32_e32 v102, v112, v112
	v_lshlrev_b32_e32 v110, 16, v66
	v_fmac_f32_e32 v102, v111, v111
	v_and_b32_e32 v109, 0xffff0000, v66
	v_fmac_f32_e32 v102, v110, v110
	v_lshlrev_b32_e32 v108, 16, v67
	v_fmac_f32_e32 v102, v109, v109
	v_and_b32_e32 v1, 0xffff0000, v67
	v_fmac_f32_e32 v102, v108, v108
	v_and_b32_e32 v2, 0xffff0000, v60
	v_lshlrev_b32_e32 v3, 16, v60
	v_fmac_f32_e32 v102, v1, v1
	v_pk_mul_f32 v[100:101], v[2:3], v[2:3]
	s_mov_b32 s0, 0x800000
	v_add_f32_e32 v101, v101, v102
	v_add_f32_e32 v104, v100, v101
	v_and_b32_e32 v100, 0xffff0000, v61
	v_lshlrev_b32_e32 v101, 16, v61
	v_pk_mul_f32 v[102:103], v[100:101], v[100:101]
	s_nop 0
	v_add_f32_e32 v103, v103, v104
	v_add_f32_e32 v106, v102, v103
	v_and_b32_e32 v102, 0xffff0000, v62
	v_lshlrev_b32_e32 v103, 16, v62
	v_pk_mul_f32 v[104:105], v[102:103], v[102:103]
	s_nop 0
	v_add_f32_e32 v105, v105, v106
	v_add_f32_e32 v115, v104, v105
	v_and_b32_e32 v104, 0xffff0000, v63
	v_lshlrev_b32_e32 v105, 16, v63
	v_pk_mul_f32 v[106:107], v[104:105], v[104:105]
	s_nop 0
	v_add_f32_e32 v107, v107, v115
	v_add_f32_e32 v106, v106, v107
	s_nop 1
	v_add_f32_dpp v106, v106, v106 quad_perm:[1,0,3,2] row_mask:0xf bank_mask:0xf
	s_nop 1
	v_add_f32_dpp v106, v106, v106 quad_perm:[2,3,0,1] row_mask:0xf bank_mask:0xf
	s_nop 1
	v_add_f32_dpp v106, v106, v106 row_half_mirror row_mask:0xf bank_mask:0xf
	s_nop 0
	v_fmamk_f32 v106, v106, 0x3c000000, v221
	v_mul_f32_e32 v107, 0x4b800000, v106
	v_cmp_gt_f32_e32 vcc, s0, v106
	s_nop 1
	v_cndmask_b32_e32 v106, v106, v107, vcc
	v_rsq_f32_e32 v106, v106
	s_nop 0
	v_mul_f32_e32 v107, 0x45800000, v106
	v_cndmask_b32_e32 v106, v106, v107, vcc
	v_mul_f32_e32 v100, v106, v100
	v_mul_f32_e32 v115, v31, v100
	v_mul_f32_e32 v100, v106, v103
	v_mul_f32_e32 v116, v24, v100
	v_mul_f32_e32 v100, v106, v102
	v_mul_f32_e32 v107, v106, v114
	v_mul_f32_e32 v117, v25, v100
	v_mul_f32_e32 v100, v106, v105
	v_mul_f32_e32 v107, v36, v107
	v_mul_f32_e32 v113, v106, v113
	v_mul_f32_e32 v112, v106, v112
	v_mul_f32_e32 v111, v106, v111
	v_mul_f32_e32 v110, v106, v110
	v_mul_f32_e32 v109, v106, v109
	v_mul_f32_e32 v108, v106, v108
	v_mul_f32_e32 v1, v106, v1
	v_mul_f32_e32 v3, v106, v3
	v_mul_f32_e32 v2, v106, v2
	v_mul_f32_e32 v101, v106, v101
	v_mul_f32_e32 v118, v26, v100
	v_mul_f32_e32 v100, v106, v104
	v_mul_f32_e32 v113, v37, v113
	v_mul_f32_e32 v112, v38, v112
	v_mul_f32_e32 v111, v39, v111
	v_mul_f32_e32 v110, v32, v110
	v_mul_f32_e32 v109, v33, v109
	v_mul_f32_e32 v108, v34, v108
	v_mul_f32_e32 v1, v35, v1
	v_mul_f32_e32 v3, v28, v3
	v_mul_f32_e32 v2, v29, v2
	v_mul_f32_e32 v114, v30, v101
	v_mul_f32_e32 v119, v27, v100
	v_cvt_pk_bf16_f32 v100, v107, v113
	v_cvt_pk_bf16_f32 v101, v112, v111
	v_cvt_pk_bf16_f32 v102, v110, v109
	v_cvt_pk_bf16_f32 v103, v108, v1
	v_cvt_pk_bf16_f32 v104, v3, v2
	v_cvt_pk_bf16_f32 v105, v114, v115
	v_cvt_pk_bf16_f32 v106, v116, v117
	v_cvt_pk_bf16_f32 v107, v118, v119

.LBB0_661:
	s_and_saveexec_b64 s[4:5], s[16:17]
	s_cbranch_execz .LBB0_558
	v_add_u32_e32 v1, v166, v168
	v_readfirstlane_b32 s16, v180
	v_mov_b64_e32 v[114:115], 0
	v_mov_b64_e32 v[116:117], 0
	v_mov_b64_e32 v[104:105], 0
	v_mov_b64_e32 v[106:107], 0
	v_mov_b64_e32 v[108:109], 0
	v_mov_b64_e32 v[110:111], 0
	v_mov_b64_e32 v[100:101], 0
	v_mov_b64_e32 v[102:103], 0
	s_bitcmp1_b32 s16, 0
	s_cbranch_scc0 .Lal_q0_b
	ds_read_b128 v[182:185], v1 offset:36864
	ds_read_b128 v[186:189], v1 offset:36928
	ds_read_b128 v[190:193], v1 offset:36992
	ds_read_b128 v[204:207], v1 offset:37056
	s_waitcnt lgkmcnt(3)
	v_mfma_f32_16x16x32_bf16 v[114:117], v[182:185], v[80:83], 0
	s_waitcnt lgkmcnt(2)
	v_mfma_f32_16x16x32_bf16 v[114:117], v[186:189], v[84:87], v[114:117]
	s_waitcnt lgkmcnt(1)
	v_mfma_f32_16x16x32_bf16 v[114:117], v[190:193], v[88:91], v[114:117]
	s_waitcnt lgkmcnt(0)
	v_mfma_f32_16x16x32_bf16 v[114:117], v[204:207], v[92:95], v[114:117]
.Lal_q0_b:
	s_bitcmp1_b32 s16, 1
	s_cbranch_scc0 .Lal_q1_b
	ds_read_b128 v[208:211], v1 offset:41216
	ds_read_b128 v[212:215], v1 offset:41280
	ds_read_b128 v[216:219], v1 offset:41344
	ds_read_b128 v[118:121], v1 offset:41408
	s_waitcnt lgkmcnt(3)
	v_mfma_f32_16x16x32_bf16 v[104:107], v[208:211], v[80:83], 0
	s_waitcnt lgkmcnt(2)
	v_mfma_f32_16x16x32_bf16 v[104:107], v[212:215], v[84:87], v[104:107]
	s_waitcnt lgkmcnt(1)
	v_mfma_f32_16x16x32_bf16 v[104:107], v[216:219], v[88:91], v[104:107]
	s_waitcnt lgkmcnt(0)
	v_mfma_f32_16x16x32_bf16 v[104:107], v[118:121], v[92:95], v[104:107]
.Lal_q1_b:
	s_bitcmp1_b32 s16, 2
	s_cbranch_scc0 .Lal_q2_b
	ds_read_b128 v[182:185], v1 offset:45568
	ds_read_b128 v[186:189], v1 offset:45632
	ds_read_b128 v[190:193], v1 offset:45696
	ds_read_b128 v[204:207], v1 offset:45760
	s_waitcnt lgkmcnt(3)
	v_mfma_f32_16x16x32_bf16 v[108:111], v[182:185], v[80:83], 0
	s_waitcnt lgkmcnt(2)
	v_mfma_f32_16x16x32_bf16 v[108:111], v[186:189], v[84:87], v[108:111]
	s_waitcnt lgkmcnt(1)
	v_mfma_f32_16x16x32_bf16 v[108:111], v[190:193], v[88:91], v[108:111]
	s_waitcnt lgkmcnt(0)
	v_mfma_f32_16x16x32_bf16 v[108:111], v[204:207], v[92:95], v[108:111]
.Lal_q2_b:
	s_bitcmp1_b32 s16, 3
	s_cbranch_scc0 .Lal_q3_b
	ds_read_b128 v[208:211], v1 offset:49920
	ds_read_b128 v[212:215], v1 offset:49984
	ds_read_b128 v[216:219], v1 offset:50048
	ds_read_b128 v[118:121], v1 offset:50112
	s_waitcnt lgkmcnt(3)
	v_mfma_f32_16x16x32_bf16 v[100:103], v[208:211], v[80:83], 0
	s_waitcnt lgkmcnt(2)
	v_mfma_f32_16x16x32_bf16 v[100:103], v[212:215], v[84:87], v[100:103]
	s_waitcnt lgkmcnt(1)
	v_mfma_f32_16x16x32_bf16 v[100:103], v[216:219], v[88:91], v[100:103]
	s_waitcnt lgkmcnt(0)
	v_mfma_f32_16x16x32_bf16 v[100:103], v[118:121], v[92:95], v[100:103]
.Lal_q3_b:
	s_and_b64 vcc, exec, s[0:1]
	s_cbranch_vccnz .Lal_nowin_b
	s_mov_b32 s17, 0x1241c
	v_add3_u32 v3, v177, v176, s17
	ds_read_b32 v122, v3
	ds_read_b32 v123, v3 offset:4
	ds_read_b32 v124, v3 offset:8
	ds_read_b32 v125, v3 offset:12
	ds_read_b32 v126, v3 offset:64
	ds_read_b32 v127, v3 offset:68
	ds_read_b32 v128, v3 offset:72
	ds_read_b32 v129, v3 offset:76
	ds_read_b32 v182, v3 offset:128
	ds_read_b32 v183, v3 offset:132
	ds_read_b32 v184, v3 offset:136
	ds_read_b32 v185, v3 offset:140
	ds_read_b32 v186, v3 offset:192
	ds_read_b32 v187, v3 offset:196
	ds_read_b32 v188, v3 offset:200
	ds_read_b32 v189, v3 offset:204
	v_mov_b32_e32 v2, 0xf149f2ca
	s_waitcnt lgkmcnt(12)
	v_add_f32_e32 v122, v114, v122
	v_add_f32_e32 v123, v115, v123
	v_add_f32_e32 v124, v116, v124
	v_add_f32_e32 v125, v117, v125
	v_cndmask_b32_e64 v114, v2, v122, s[38:39]
	v_cndmask_b32_e64 v115, v2, v123, s[40:41]
	v_cndmask_b32_e64 v116, v2, v124, s[42:43]
	v_cndmask_b32_e64 v117, v2, v125, s[44:45]
	s_waitcnt lgkmcnt(8)
	v_add_f32_e32 v126, v104, v126
	v_add_f32_e32 v127, v105, v127
	v_add_f32_e32 v128, v106, v128
	v_add_f32_e32 v129, v107, v129
	v_cndmask_b32_e64 v104, v2, v126, s[28:29]
	v_cndmask_b32_e64 v105, v2, v127, s[56:57]
	v_cndmask_b32_e64 v106, v2, v128, s[58:59]
	v_cndmask_b32_e64 v107, v2, v129, s[60:61]
	s_waitcnt lgkmcnt(4)
	v_add_f32_e32 v182, v108, v182
	v_add_f32_e32 v183, v109, v183
	v_add_f32_e32 v184, v110, v184
	v_add_f32_e32 v185, v111, v185
	v_cndmask_b32_e64 v108, v2, v182, s[36:37]
	v_cndmask_b32_e64 v109, v2, v183, s[62:63]
	v_cndmask_b32_e64 v110, v2, v184, s[64:65]
	v_cndmask_b32_e64 v111, v2, v185, s[2:3]
	s_waitcnt lgkmcnt(0)
	v_add_f32_e32 v186, v100, v186
	v_add_f32_e32 v187, v101, v187
	v_add_f32_e32 v188, v102, v188
	v_add_f32_e32 v189, v103, v189
	v_cndmask_b32_e64 v100, v2, v186, s[46:47]
	v_cndmask_b32_e64 v101, v2, v187, s[48:49]
	v_cndmask_b32_e64 v102, v2, v188, s[50:51]
	v_cndmask_b32_e64 v103, v2, v189, s[52:53]
	s_branch .Lal_sm_b

.Lal_sm_b:
	s_mov_b32 s0, 0xf149f2ca
	v_max3_f32 v1, v114, s0, v115
	v_max3_f32 v1, v1, v116, v117
	v_max3_f32 v1, v1, v104, v105
	v_max3_f32 v1, v1, v106, v107
	v_max3_f32 v1, v1, v108, v109
	v_max3_f32 v1, v1, v110, v111
	v_max3_f32 v1, v1, v100, v101
	v_max3_f32 v1, v1, v102, v103
	ds_bpermute_b32 v2, v159, v1
	s_waitcnt lgkmcnt(0)
	v_max_f32_e32 v2, v2, v2
	v_max_f32_e32 v1, v1, v2
	ds_bpermute_b32 v2, v158, v1
	s_waitcnt lgkmcnt(0)
	v_max3_f32 v1, v179, v1, v2
	v_sub_f32_e32 v3, v114, v1
	v_exp_f32_e32 v112, v3
	v_sub_f32_e32 v3, v105, v1
	v_sub_f32_e32 v113, v115, v1
	v_sub_f32_e32 v115, v117, v1
	v_exp_f32_e32 v117, v3
	v_sub_f32_e32 v3, v106, v1
	v_exp_f32_e32 v118, v3
	v_sub_f32_e32 v3, v107, v1
	v_exp_f32_e32 v119, v3
	v_sub_f32_e32 v3, v108, v1
	v_exp_f32_e32 v108, v3
	v_sub_f32_e32 v3, v109, v1
	v_exp_f32_e32 v109, v3
	v_sub_f32_e32 v3, v110, v1
	v_exp_f32_e32 v110, v3
	v_sub_f32_e32 v3, v111, v1
	v_exp_f32_e32 v111, v3
	v_sub_f32_e32 v3, v100, v1
	v_sub_f32_e32 v2, v179, v1
	v_exp_f32_e32 v120, v3
	v_sub_f32_e32 v3, v101, v1
	v_exp_f32_e32 v121, v3
	v_sub_f32_e32 v3, v102, v1
	v_exp_f32_e32 v2, v2
	v_sub_f32_e32 v114, v116, v1
	v_sub_f32_e32 v104, v104, v1
	v_exp_f32_e32 v122, v3
	v_sub_f32_e32 v3, v103, v1
	v_exp_f32_e32 v113, v113
	v_exp_f32_e32 v114, v114
	v_exp_f32_e32 v115, v115
	v_exp_f32_e32 v116, v104
	v_exp_f32_e32 v123, v3
	v_pk_mul_f32 v[98:99], v[98:99], v[2:3] op_sel_hi:[1,0]
	v_pk_mul_f32 v[96:97], v[96:97], v[2:3] op_sel_hi:[1,0]
	v_cvt_pk_bf16_f32 v104, v112, v113
	v_cvt_pk_bf16_f32 v105, v114, v115
	v_cvt_pk_bf16_f32 v106, v116, v117
	v_cvt_pk_bf16_f32 v107, v118, v119
	v_cvt_pk_bf16_f32 v100, v108, v109
	v_cvt_pk_bf16_f32 v101, v110, v111
	v_cvt_pk_bf16_f32 v102, v120, v121
	v_cvt_pk_bf16_f32 v103, v122, v123
	v_add_f32_e32 v3, 0, v112
	v_add_f32_e32 v3, v113, v3
	v_add_f32_e32 v3, v114, v3
	v_add_f32_e32 v3, v115, v3
	v_add_f32_e32 v3, v116, v3
	v_add_f32_e32 v3, v117, v3
	v_add_f32_e32 v3, v118, v3
	v_add_f32_e32 v3, v119, v3
	v_add_f32_e32 v3, v108, v3
	v_add_f32_e32 v3, v109, v3
	v_add_f32_e32 v3, v110, v3
	v_add_f32_e32 v3, v111, v3
	v_add_f32_e32 v3, v120, v3
	v_add_f32_e32 v3, v121, v3
	v_add_f32_e32 v3, v122, v3
	v_add_f32_e32 v3, v123, v3
	v_fmac_f32_e32 v3, v171, v2
	v_mov_b32_e32 v179, v1
	v_mov_b32_e32 v171, v3
	v_pk_mul_f32 v[78:79], v[78:79], v[2:3] op_sel_hi:[1,0]
	v_pk_mul_f32 v[76:77], v[76:77], v[2:3] op_sel_hi:[1,0]
	v_pk_mul_f32 v[42:43], v[42:43], v[2:3] op_sel_hi:[1,0]
	v_pk_mul_f32 v[40:41], v[40:41], v[2:3] op_sel_hi:[1,0]
	v_pk_mul_f32 v[22:23], v[22:23], v[2:3] op_sel_hi:[1,0]
	v_pk_mul_f32 v[20:21], v[20:21], v[2:3] op_sel_hi:[1,0]
	v_pk_mul_f32 v[18:19], v[18:19], v[2:3] op_sel_hi:[1,0]
	v_pk_mul_f32 v[16:17], v[16:17], v[2:3] op_sel_hi:[1,0]
	v_pk_mul_f32 v[14:15], v[14:15], v[2:3] op_sel_hi:[1,0]
	v_pk_mul_f32 v[12:13], v[12:13], v[2:3] op_sel_hi:[1,0]
	v_pk_mul_f32 v[10:11], v[10:11], v[2:3] op_sel_hi:[1,0]
	v_pk_mul_f32 v[8:9], v[8:9], v[2:3] op_sel_hi:[1,0]
	v_pk_mul_f32 v[6:7], v[6:7], v[2:3] op_sel_hi:[1,0]
	v_pk_mul_f32 v[4:5], v[4:5], v[2:3] op_sel_hi:[1,0]
	v_add_u32_e32 v1, 54272, v169
	s_and_b32 s17, s16, 3
	s_cmp_eq_u32 s17, 0
	s_cbranch_scc1 .Lal_pv1only_b
	s_and_b32 s17, s16, 12
	s_cmp_eq_u32 s17, 0
	s_cbranch_scc1 .Lal_pv0only_b
	v_add_u32_e32 v3, 0, v1
	ds_read2_b64 v[182:185], v3 offset0:0 offset1:4
	v_add_u32_e32 v3, 2304, v1
	ds_read2_b64 v[186:189], v3 offset0:0 offset1:4
	v_add_u32_e32 v3, 4608, v1
	ds_read2_b64 v[190:193], v3 offset0:0 offset1:4
	v_add_u32_e32 v3, 6912, v1
	ds_read2_b64 v[204:207], v3 offset0:0 offset1:4
	v_add_u32_e32 v3, 9216, v1
	ds_read2_b64 v[208:211], v3 offset0:0 offset1:4
	v_add_u32_e32 v3, 11520, v1
	ds_read2_b64 v[212:215], v3 offset0:0 offset1:4
	v_add_u32_e32 v3, 13824, v1
	ds_read2_b64 v[216:219], v3 offset0:0 offset1:4
	v_add_u32_e32 v3, 16128, v1
	ds_read2_b64 v[118:121], v3 offset0:0 offset1:4
	s_waitcnt lgkmcnt(7)
	v_mfma_f32_16x16x32_bf16 v[96:99], v[182:185], v[104:107], v[96:99]
	v_add_u32_e32 v3, 0, v1
	ds_read2_b64 v[182:185], v3 offset0:8 offset1:12
	s_waitcnt lgkmcnt(7)
	v_mfma_f32_16x16x32_bf16 v[76:79], v[186:189], v[104:107], v[76:79]
	v_add_u32_e32 v3, 2304, v1
	ds_read2_b64 v[186:189], v3 offset0:8 offset1:12
	s_waitcnt lgkmcnt(7)
	v_mfma_f32_16x16x32_bf16 v[40:43], v[190:193], v[104:107], v[40:43]
	v_add_u32_e32 v3, 4608, v1
	ds_read2_b64 v[190:193], v3 offset0:8 offset1:12
	s_waitcnt lgkmcnt(7)
	v_mfma_f32_16x16x32_bf16 v[20:23], v[204:207], v[104:107], v[20:23]
	v_add_u32_e32 v3, 6912, v1
	ds_read2_b64 v[204:207], v3 offset0:8 offset1:12
	s_waitcnt lgkmcnt(7)
	v_mfma_f32_16x16x32_bf16 v[16:19], v[208:211], v[104:107], v[16:19]
	v_add_u32_e32 v3, 9216, v1
	ds_read2_b64 v[208:211], v3 offset0:8 offset1:12
	s_waitcnt lgkmcnt(7)
	v_mfma_f32_16x16x32_bf16 v[12:15], v[212:215], v[104:107], v[12:15]
	v_add_u32_e32 v3, 11520, v1
	ds_read2_b64 v[212:215], v3 offset0:8 offset1:12
	s_waitcnt lgkmcnt(7)
	v_mfma_f32_16x16x32_bf16 v[8:11], v[216:219], v[104:107], v[8:11]
	v_add_u32_e32 v3, 13824, v1
	ds_read2_b64 v[216:219], v3 offset0:8 offset1:12
	s_waitcnt lgkmcnt(7)
	v_mfma_f32_16x16x32_bf16 v[4:7], v[118:121], v[104:107], v[4:7]
	v_add_u32_e32 v3, 16128, v1
	ds_read2_b64 v[118:121], v3 offset0:8 offset1:12
	s_waitcnt lgkmcnt(7)
	v_mfma_f32_16x16x32_bf16 v[96:99], v[182:185], v[100:103], v[96:99]
	s_waitcnt lgkmcnt(6)
	v_mfma_f32_16x16x32_bf16 v[76:79], v[186:189], v[100:103], v[76:79]
	s_waitcnt lgkmcnt(5)
	v_mfma_f32_16x16x32_bf16 v[40:43], v[190:193], v[100:103], v[40:43]
	s_waitcnt lgkmcnt(4)
	v_mfma_f32_16x16x32_bf16 v[20:23], v[204:207], v[100:103], v[20:23]
	s_waitcnt lgkmcnt(3)
	v_mfma_f32_16x16x32_bf16 v[16:19], v[208:211], v[100:103], v[16:19]
	s_waitcnt lgkmcnt(2)
	v_mfma_f32_16x16x32_bf16 v[12:15], v[212:215], v[100:103], v[12:15]
	s_waitcnt lgkmcnt(1)
	v_mfma_f32_16x16x32_bf16 v[8:11], v[216:219], v[100:103], v[8:11]
	s_waitcnt lgkmcnt(0)
	v_mfma_f32_16x16x32_bf16 v[4:7], v[118:121], v[100:103], v[4:7]
	s_branch .Lal_pvdone_b

.Lal_pvdone_b:
	s_branch .LBB0_558
.LBB0_736:
	s_mov_b64 s[0:1], 0

.LBB0_742:
	s_or_b64 exec, exec, s[2:3]
	s_lshl_b32 s2, s34, 11
	v_add_lshl_u32 v10, s2, v19, 1
	v_mov_b32_e32 v11, v0
	v_lshl_add_u64 v[10:11], s[78:79], 0, v[10:11]
	v_mov_b32_e32 v27, v0
	v_lshl_add_u64 v[10:11], v[10:11], 0, v[26:27]
	v_mov_b32_e32 v29, v0
	v_lshl_add_u64 v[10:11], v[10:11], 0, v[28:29]
	s_mov_b64 s[2:3], 0x600000
	v_lshl_add_u64 v[10:11], v[10:11], 0, s[2:3]
	s_lshl_b64 s[2:3], s[34:35], 12
	v_lshl_add_u64 v[34:35], v[24:25], 0, s[2:3]
	v_lshl_add_u64 v[12:13], v[20:21], 1, v[10:11]
	v_lshl_add_u64 v[10:11], v[22:23], 1, v[10:11]
	v_lshl_add_u64 v[40:41], v[14:15], 1, v[34:35]
	global_load_dwordx2 v[32:33], v[12:13], off
	global_load_dwordx2 v[30:31], v[10:11], off
	s_barrier
	global_load_dwordx4 v[10:13], v[40:41], off
	s_and_saveexec_b64 s[2:3], s[40:41]
	s_cbranch_execz .LBB0_744
	v_lshl_add_u64 v[36:37], v[16:17], 1, v[34:35]
	global_load_ushort v27, v[36:37], off offset:-2
	s_waitcnt vmcnt(0)
	v_lshlrev_b32_e32 v37, 16, v27
